# also: scan sample chains issue their state_wkv loads before wave 0's preparation instead of after the second barrier
# speedup vs baseline: 1.0532x; 1.0023x over previous
.LBB0_1187:
	s_ashr_i32 s8, s10, 4
	s_add_i32 s12, s8, 0x4000
	s_and_b32 s17, s10, 15
	s_ashr_i32 s13, s12, 31
	s_and_b64 vcc, exec, s[0:1]
	s_cbranch_vccnz .Lsce_w0
	s_ashr_i32 vcc_hi, s10, 31
	s_mov_b32 vcc_lo, s10
	s_lshl_b64 vcc, vcc, 12
	v_lshl_add_u64 v[208:209], vcc, 0, v[2:3]
	v_lshlrev_b64 v[208:209], 2, v[208:209]
	v_lshl_add_u64 v[208:209], v[6:7], 0, v[208:209]
	global_load_dwordx4 v[200:203], v[208:209], off
	global_load_dwordx4 v[204:207], v[208:209], off offset:16
.Lsce_w0:
	s_waitcnt lgkmcnt(0)
	s_barrier
	s_and_saveexec_b64 s[14:15], s[0:1]
	s_cbranch_execz .LBB0_1190
	v_lshl_or_b32 v4, s17, 6, v19
	v_lshlrev_b64 v[22:23], 1, v[4:5]
	s_lshl_b64 s[8:9], s[12:13], 11
	v_or_b32_e32 v23, s9, v23
	v_or_b32_e32 v22, s8, v22
	v_lshl_add_u64 v[24:25], s[62:63], 0, v[22:23]
	global_load_ushort v30, v[24:25], off
	v_lshlrev_b64 v[24:25], 2, v[4:5]
	v_lshl_add_u64 v[26:27], s[20:21], 0, v[24:25]
	global_load_dword v4, v[26:27], off
	v_lshl_add_u64 v[26:27], s[96:97], 0, v[22:23]
	v_lshl_add_u64 v[28:29], s[66:67], 0, v[22:23]
	global_load_ushort v31, v[26:27], off
	s_nop 0
	global_load_ushort v28, v[28:29], off
	v_lshl_add_u64 v[26:27], s[22:23], 0, v[24:25]
	global_load_dword v26, v[26:27], off
	v_lshl_add_u64 v[24:25], s[24:25], 0, v[24:25]
	global_load_dword v27, v[24:25], off
	v_lshl_add_u64 v[24:25], s[28:29], 0, v[22:23]
	global_load_ushort v24, v[24:25], off
	v_lshl_add_u64 v[22:23], s[54:55], 0, v[22:23]
	global_load_ushort v22, v[22:23], off
	s_ashr_i32 vcc_hi, s10, 31
	s_mov_b32 vcc_lo, s10
	s_lshl_b64 vcc, vcc, 12
	v_lshl_add_u64 v[208:209], vcc, 0, v[2:3]
	v_lshlrev_b64 v[208:209], 2, v[208:209]
	v_lshl_add_u64 v[208:209], v[6:7], 0, v[208:209]
	global_load_dwordx4 v[200:203], v[208:209], off
	global_load_dwordx4 v[204:207], v[208:209], off offset:16
	s_waitcnt vmcnt(9)
	v_lshlrev_b32_e32 v23, 16, v30
	s_waitcnt vmcnt(8)
	v_mul_f32_e32 v25, v4, v23
	v_mul_f32_e32 v4, v25, v25
	ds_bpermute_b32 v4, v16, v4
	s_waitcnt vmcnt(6)
	v_lshlrev_b32_e32 v28, 16, v28
	v_add_f32_e32 v30, -1.0, v28
	s_waitcnt vmcnt(5)
	v_fma_f32 v26, v30, v26, 1.0
	v_lshlrev_b32_e32 v29, 16, v31
	s_waitcnt lgkmcnt(0)
	v_fmac_f32_e32 v4, v25, v25
	ds_bpermute_b32 v30, v17, v4
	v_mul_f32_e32 v23, v26, v23
	v_mul_f32_e32 v26, v23, v29
	s_waitcnt vmcnt(4)
	v_mul_f32_e32 v31, v27, v26
	ds_bpermute_b32 v31, v16, v31
	s_waitcnt lgkmcnt(1)
	v_add_f32_e32 v4, v4, v30
	ds_bpermute_b32 v30, v18, v4
	s_waitcnt vmcnt(3)
	v_cvt_f32_f16_e32 v24, v24
	ds_write2st64_b32 v21, v23, v29 offset0:3 offset1:4
	s_waitcnt lgkmcnt(2)
	v_fmac_f32_e32 v31, v27, v26
	ds_bpermute_b32 v26, v17, v31
	s_waitcnt lgkmcnt(2)
	v_add_f32_e32 v4, v4, v30
	ds_bpermute_b32 v27, v14, v4
	s_waitcnt lgkmcnt(1)
	v_add_f32_e32 v26, v31, v26
	ds_bpermute_b32 v30, v18, v26
	s_waitcnt lgkmcnt(1)
	v_add_f32_e32 v4, v4, v27
	ds_bpermute_b32 v27, v13, v4
	s_waitcnt vmcnt(2)
	v_lshlrev_b32_e32 v31, 16, v22
	v_mul_f32_e32 v22, 0xbfb8aa3b, v24
	s_waitcnt lgkmcnt(1)
	v_add_f32_e32 v26, v26, v30
	ds_bpermute_b32 v30, v14, v26
	s_waitcnt lgkmcnt(1)
	v_add_f32_e32 v4, v4, v27
	ds_bpermute_b32 v27, v12, v4
	v_exp_f32_e32 v23, v22
	s_waitcnt lgkmcnt(1)
	v_add_f32_e32 v24, v26, v30
	ds_bpermute_b32 v26, v13, v24
	s_waitcnt lgkmcnt(1)
	v_add_f32_e32 v4, v4, v27
	v_mul_f32_e32 v27, 0x4f800000, v4
	v_cmp_gt_f32_e32 vcc, s3, v4
	s_nop 1
	v_cndmask_b32_e32 v27, v4, v27, vcc
	v_sqrt_f32_e32 v30, v27
	s_waitcnt lgkmcnt(0)
	v_add_f32_e32 v4, v24, v26
	v_add_u32_e32 v22, -1, v30
	v_add_u32_e32 v24, 1, v30
	v_fma_f32 v26, -v22, v30, v27
	v_fma_f32 v29, -v24, v30, v27
	v_cmp_ge_f32_e64 s[8:9], 0, v26
	s_nop 1
	v_cndmask_b32_e64 v22, v30, v22, s[8:9]
	v_cmp_lt_f32_e64 s[8:9], 0, v29
	s_nop 1
	v_cndmask_b32_e64 v22, v22, v24, s[8:9]
	v_mul_f32_e32 v24, 0x37800000, v22
	v_cndmask_b32_e32 v22, v22, v24, vcc
	v_cmp_class_f32_e32 vcc, v27, v20
	s_nop 1
	v_cndmask_b32_e32 v22, v22, v27, vcc
	v_max_f32_e32 v24, 0x2b8cbccc, v22
	v_div_scale_f32 v26, s[8:9], v24, v24, 1.0
	v_rcp_f32_e32 v27, v26
	v_div_scale_f32 v29, vcc, 1.0, v24, 1.0
	ds_bpermute_b32 v22, v12, v4
	v_fma_f32 v30, -v26, v27, 1.0
	v_fmac_f32_e32 v27, v30, v27
	v_mul_f32_e32 v30, v29, v27
	v_fma_f32 v32, -v26, v30, v29
	v_fmac_f32_e32 v30, v32, v27
	v_fma_f32 v26, -v26, v30, v29
	v_div_fmas_f32 v26, v26, v27, v30
	v_div_fixup_f32 v24, v26, v24, 1.0
	v_mul_f32_e64 v26, v24, -v25
	v_mul_f32_e32 v24, v25, v24
	v_mul_f32_e32 v24, v24, v28
	ds_write_b32 v10, v26
	ds_write2st64_b32 v21, v23, v24 offset0:1 offset1:2
	ds_write_b32 v21, v31 offset:1280
	s_and_b64 exec, exec, s[6:7]
	s_cbranch_execz .LBB0_1190
	s_lshl_b64 s[8:9], s[12:13], 6
	s_add_u32 s8, s58, s8
	s_addc_u32 s9, s59, s9
	s_lshl_b32 s11, s17, 2
	s_waitcnt lgkmcnt(3)
	v_add_f32_e32 v4, v4, v22
	v_mov_b32_e32 v22, s11
	global_store_dword v22, v4, s[8:9]
.LBB0_1190:
	s_or_b64 exec, exec, s[14:15]
	s_ashr_i32 s11, s10, 31
	s_lshl_b64 s[8:9], s[10:11], 12
	s_waitcnt lgkmcnt(3)
	v_lshl_add_u64 v[22:23], s[8:9], 0, v[2:3]
	v_lshlrev_b64 v[62:63], 2, v[22:23]
	v_lshl_add_u64 v[26:27], v[6:7], 0, v[62:63]
	s_waitcnt lgkmcnt(0)
	s_barrier
	ds_read_b128 v[30:33], v11
	ds_read_b128 v[34:37], v11 offset:16
	s_waitcnt vmcnt(1) lgkmcnt(1)
	v_pk_mul_f32 v[30:31], v[200:201], v[30:31]
	s_nop 0
	v_add_f32_e32 v4, 0, v30
	v_pk_mul_f32 v[32:33], v[202:203], v[32:33]
	v_add_f32_e32 v4, v4, v31
	v_add_f32_e32 v4, v4, v32
	s_waitcnt vmcnt(0) lgkmcnt(0)
	v_pk_mul_f32 v[34:35], v[204:205], v[34:35]
	v_add_f32_e32 v4, v4, v33
	v_add_f32_e32 v4, v4, v34
	v_pk_mul_f32 v[36:37], v[206:207], v[36:37]
	v_add_f32_e32 v4, v4, v35
	v_add_f32_e32 v4, v4, v36
	v_add_f32_e32 v30, v4, v37
	ds_bpermute_b32 v31, v12, v30
	ds_read_b32 v4, v15 offset:1280
	s_waitcnt lgkmcnt(1)
	v_add_f32_e32 v46, v30, v31
	ds_bpermute_b32 v47, v13, v46
	ds_read_b128 v[30:33], v11 offset:1024
	ds_read_b128 v[34:37], v11 offset:1040
	ds_read_b128 v[38:41], v11 offset:256
	ds_read_b128 v[42:45], v11 offset:272
	s_waitcnt lgkmcnt(4)
	v_add_f32_e32 v64, v46, v47
	ds_bpermute_b32 v65, v14, v64
	ds_read_b128 v[46:49], v11 offset:512
	ds_read_b128 v[50:53], v11 offset:528
	ds_read_b128 v[54:57], v11 offset:768
	ds_read_b128 v[58:61], v11 offset:784
	s_waitcnt lgkmcnt(4)
	v_add_f32_e32 v64, v64, v65
	s_waitcnt lgkmcnt(3)
	v_pk_mul_f32 v[46:47], v[64:65], v[46:47] op_sel_hi:[0,1]
	v_pk_mul_f32 v[48:49], v[64:65], v[48:49] op_sel_hi:[0,1]
	v_pk_fma_f32 v[22:23], v[200:201], v[38:39], v[46:47]
	v_pk_fma_f32 v[38:39], v[202:203], v[40:41], v[48:49]
	s_waitcnt lgkmcnt(1)
	v_pk_fma_f32 v[24:25], v[4:5], v[54:55], v[22:23] op_sel_hi:[0,1,1]
	v_pk_mul_f32 v[50:51], v[64:65], v[50:51] op_sel_hi:[0,1]
	v_fma_f32 v22, v30, v24, 0
	v_pk_fma_f32 v[40:41], v[204:205], v[42:43], v[50:51]
	v_pk_fma_f32 v[26:27], v[4:5], v[56:57], v[38:39] op_sel_hi:[0,1,1]
	v_fmac_f32_e32 v22, v31, v25
	v_pk_mul_f32 v[52:53], v[64:65], v[52:53] op_sel_hi:[0,1]
	v_fmac_f32_e32 v22, v32, v26
	v_pk_fma_f32 v[42:43], v[206:207], v[44:45], v[52:53]
	s_waitcnt lgkmcnt(0)
	v_pk_fma_f32 v[28:29], v[4:5], v[58:59], v[40:41] op_sel_hi:[0,1,1]
	v_fmac_f32_e32 v22, v33, v27
	v_fmac_f32_e32 v22, v34, v28
	v_fmac_f32_e32 v22, v35, v29
	v_pk_fma_f32 v[30:31], v[4:5], v[60:61], v[42:43] op_sel_hi:[0,1,1]
	v_fmac_f32_e32 v22, v36, v30
	v_fmac_f32_e32 v22, v37, v31
	ds_bpermute_b32 v4, v12, v22
	v_lshl_add_u64 v[32:33], v[8:9], 0, v[62:63]
	global_store_dwordx4 v[32:33], v[24:27], off
	global_store_dwordx4 v[32:33], v[28:31], off offset:16
	s_waitcnt lgkmcnt(0)
	v_add_f32_e32 v4, v22, v4
	ds_bpermute_b32 v22, v13, v4
	s_waitcnt lgkmcnt(0)
	v_add_f32_e32 v4, v4, v22
	ds_bpermute_b32 v22, v14, v4
	s_and_saveexec_b64 s[8:9], s[4:5]
	s_cbranch_execz .LBB0_1186
	s_mul_hi_i32 s11, s12, 0x880
	s_mulk_i32 s12, 0x880
	s_add_u32 s12, s88, s12
	s_addc_u32 s11, s89, s11
	s_lshl_b32 s13, s17, 7
	s_waitcnt lgkmcnt(0)
	v_add_f32_e32 v4, v4, v22
	s_add_u32 s12, s12, s13
	v_bfe_u32 v22, v4, 16, 1
	s_addc_u32 s13, s11, 0
	v_add3_u32 v4, v4, v22, s16
	v_lshl_add_u64 v[22:23], v[0:1], 1, s[12:13]
	global_store_short_d16_hi v[22:23], v4, off
	s_branch .LBB0_1186
